# scan producers: groupnorm partial sums moved from wave 7 to wave 5 to balance the SIMD sharing
# baseline (speedup 1.0000x reference)
.LBB0_999:
	v_cndmask_b32_e64 v80, 0, 1, s[36:37]
	v_cmp_ne_u32_e64 s[14:15], 1, v80
	s_cmp_eq_u32 s80, 5
	s_cbranch_scc1 .LBB0_1002
	s_andn2_b64 vcc, exec, s[36:37]
	s_cbranch_vccnz .LBB0_1013
	s_cmp_gt_i32 s91, 1
	s_cselect_b64 s[18:19], -1, 0
	s_cmp_lt_i32 s91, 2
	s_cbranch_scc1 .LBB0_1002
	s_add_i32 s16, s91, 6
	s_and_b32 s16, s16, 7
	s_or_b32 s16, s16, s81
	s_ashr_i32 s17, s16, 31
	s_lshl_b64 s[16:17], s[16:17], 10
	s_waitcnt lgkmcnt(0)
	v_lshl_add_u64 v[80:81], v[152:153], 0, s[16:17]
	global_load_dwordx2 v[158:159], v[80:81], off sc1
	global_load_dwordx2 v[160:161], v[80:81], off offset:512 sc1
.LBB0_1002:
	s_cmp_eq_u32 s80, 7
	s_cbranch_scc1 .LBB0_1004
	s_cmp_lt_i32 s91, 1
	s_cbranch_scc1 .LBB0_1004
	s_add_i32 s16, s91, -1
	s_lshl_b32 s17, s16, 12
	s_and_b32 s17, s17, 0x3000
	v_add_u32_e32 v92, s17, v179
	s_waitcnt lgkmcnt(0)
	ds_read_b128 v[80:83], v92
	ds_read_b128 v[84:87], v92 offset:16
	ds_read_b128 v[88:91], v92 offset:32
	ds_read_b128 v[92:95], v92 offset:48
	s_lshl_b32 s16, s16, 1
	s_waitcnt lgkmcnt(0)
	v_mov_b32_e32 v96, v81
	v_mov_b32_e32 v97, v82
	v_mov_b32_e32 v98, v80
	v_mov_b32_e32 v99, v83
	v_pk_mul_f32 v[82:83], v[82:83], v[82:83]
	v_pk_mul_f32 v[80:81], v[80:81], v[80:81]
	v_pk_add_f32 v[96:97], v[96:97], v[98:99]
	v_pk_mov_b32 v[98:99], v[80:81], v[82:83] op_sel:[1,0]
	v_mov_b32_e32 v81, v83
	v_pk_add_f32 v[80:81], v[98:99], v[80:81]
	v_mov_b32_e32 v82, v85
	v_mov_b32_e32 v83, v86
	v_mov_b32_e32 v98, v84
	v_mov_b32_e32 v99, v87
	v_pk_add_f32 v[82:83], v[82:83], v[98:99]
	v_pk_mul_f32 v[86:87], v[86:87], v[86:87]
	v_pk_mul_f32 v[84:85], v[84:85], v[84:85]
	v_add_f32_e32 v96, v96, v97
	v_pk_add_f32 v[82:83], v[82:83], v[82:83] op_sel:[0,1] op_sel_hi:[1,0]
	v_pk_mov_b32 v[98:99], v[84:85], v[86:87] op_sel:[1,0]
	v_mov_b32_e32 v85, v87
	v_add_f32_e32 v96, 0, v96
	v_pk_add_f32 v[84:85], v[98:99], v[84:85]
	v_add_f32_e32 v86, v88, v89
	v_add_f32_e32 v98, v90, v91
	v_mov_b32_e32 v97, v92
	v_mov_b32_e32 v83, v93
	v_mov_b32_e32 v87, v94
	v_mov_b32_e32 v99, v95
	v_pk_add_f32 v[82:83], v[96:97], v[82:83]
	v_pk_add_f32 v[86:87], v[86:87], v[98:99]
	v_pk_add_f32 v[80:81], v[80:81], v[80:81] op_sel:[0,1] op_sel_hi:[1,0]
	v_pk_add_f32 v[82:83], v[82:83], v[86:87]
	v_mul_f32_e32 v87, v93, v93
	v_add_f32_e32 v86, v82, v83
	v_mul_f32_e32 v82, v92, v92
	v_mov_b32_e32 v81, v82
	v_pk_add_f32 v[82:83], v[84:85], v[84:85] op_sel:[0,1] op_sel_hi:[1,0]
	v_mul_f32_e32 v84, v91, v91
	v_mov_b32_e32 v83, v87
	v_pk_add_f32 v[80:81], v[80:81], v[82:83]
	v_mul_f32_e32 v82, v89, v89
	v_mul_f32_e32 v92, v94, v94
	v_mul_f32_e32 v93, v95, v95
	v_pk_fma_f32 v[82:83], v[88:89], v[88:89], v[82:83] op_sel_hi:[1,1,0]
	v_pk_fma_f32 v[84:85], v[90:91], v[90:91], v[84:85] op_sel_hi:[1,1,0]
	v_mov_b32_e32 v83, v92
	v_mov_b32_e32 v85, v93
	v_pk_add_f32 v[82:83], v[82:83], v[84:85]
	s_and_b32 s16, s16, 14
	v_pk_add_f32 v[80:81], v[80:81], v[82:83]
	s_or_b32 s16, s16, s63
	v_add_f32_e32 v80, v80, v81
	s_ashr_i32 s17, s16, 31
	v_add_f32_dpp v82, v86, v86 quad_perm:[1,0,3,2] row_mask:0xf bank_mask:0xf bound_ctrl:1
	v_add_f32_dpp v83, v80, v80 quad_perm:[1,0,3,2] row_mask:0xf bank_mask:0xf bound_ctrl:1
	s_add_i32 s40, s91, s21
	s_lshl_b64 s[16:17], s[16:17], 9
	v_lshl_add_u64 v[80:81], v[154:155], 0, s[16:17]
	v_cndmask_b32_e64 v82, v83, v82, s[12:13]
	v_mov_b32_e32 v83, s40
	global_store_dwordx2 v[80:81], v[82:83], off sc1
.LBB0_1004:
	s_cmp_eq_u32 s80, 5
	s_cbranch_scc1 .LBB0_1013
	s_andn2_b64 vcc, exec, s[18:19]
	s_cbranch_vccnz .LBB0_1013
	s_add_i32 s16, s91, -2
	s_and_b32 s18, s16, 7
	s_or_b32 s18, s18, s81
	s_ashr_i32 s19, s18, 31
	s_lshl_b64 s[18:19], s[18:19], 10
	s_add_i32 s17, s16, s73
	v_lshl_add_u64 v[84:85], v[152:153], 0, s[18:19]
	s_mov_b32 s40, 0
	s_waitcnt vmcnt(0) lgkmcnt(0)
	v_mov_b64_e32 v[80:81], v[160:161]
	v_mov_b64_e32 v[82:83], v[158:159]

.LBB0_1022:
	s_cmp_eq_u32 s80, 5
	s_cbranch_scc1 .LBB0_1025
	s_and_b64 vcc, exec, s[14:15]
	s_cbranch_vccnz .LBB0_989
	s_cmp_gt_i32 s91, 0
	s_cselect_b64 s[14:15], -1, 0
	s_cmp_lt_i32 s91, 1
	s_cbranch_scc1 .LBB0_1025
	s_add_i32 s16, s91, -1
	s_and_b32 s16, s16, 7
	s_or_b32 s16, s16, s81
	s_ashr_i32 s17, s16, 31
	s_lshl_b64 s[16:17], s[16:17], 10
	s_waitcnt lgkmcnt(0)
	v_lshl_add_u64 v[80:81], v[152:153], 0, s[16:17]
	global_load_dwordx2 v[158:159], v[80:81], off sc1
	global_load_dwordx2 v[160:161], v[80:81], off offset:512 sc1
.LBB0_1025:
	s_cmp_eq_u32 s80, 7
	s_cbranch_scc1 .LBB0_1027
	s_cmp_lt_i32 s91, 0
	s_cbranch_scc1 .LBB0_1027
	s_lshl_b32 s16, s91, 12
	s_and_b32 s16, s16, 0x3000
	v_add_u32_e32 v92, s16, v179
	s_waitcnt lgkmcnt(0)
	ds_read_b128 v[80:83], v92
	ds_read_b128 v[84:87], v92 offset:16
	ds_read_b128 v[88:91], v92 offset:32
	ds_read_b128 v[92:95], v92 offset:48
	s_lshl_b32 s16, s91, 1
	s_waitcnt lgkmcnt(0)
	v_mov_b32_e32 v96, v81
	v_mov_b32_e32 v97, v82
	v_mov_b32_e32 v98, v80
	v_mov_b32_e32 v99, v83
	v_pk_mul_f32 v[82:83], v[82:83], v[82:83]
	v_pk_mul_f32 v[80:81], v[80:81], v[80:81]
	v_pk_add_f32 v[96:97], v[96:97], v[98:99]
	v_pk_mov_b32 v[98:99], v[80:81], v[82:83] op_sel:[1,0]
	v_mov_b32_e32 v81, v83
	v_pk_add_f32 v[80:81], v[98:99], v[80:81]
	v_mov_b32_e32 v82, v85
	v_mov_b32_e32 v83, v86
	v_mov_b32_e32 v98, v84
	v_mov_b32_e32 v99, v87
	v_pk_add_f32 v[82:83], v[82:83], v[98:99]
	v_pk_mul_f32 v[86:87], v[86:87], v[86:87]
	v_pk_mul_f32 v[84:85], v[84:85], v[84:85]
	v_add_f32_e32 v96, v96, v97
	v_pk_add_f32 v[82:83], v[82:83], v[82:83] op_sel:[0,1] op_sel_hi:[1,0]
	v_pk_mov_b32 v[98:99], v[84:85], v[86:87] op_sel:[1,0]
	v_mov_b32_e32 v85, v87
	v_add_f32_e32 v96, 0, v96
	v_pk_add_f32 v[84:85], v[98:99], v[84:85]
	v_add_f32_e32 v86, v88, v89
	v_add_f32_e32 v98, v90, v91
	v_mov_b32_e32 v97, v92
	v_mov_b32_e32 v83, v93
	v_mov_b32_e32 v87, v94
	v_mov_b32_e32 v99, v95
	v_pk_add_f32 v[82:83], v[96:97], v[82:83]
	v_pk_add_f32 v[86:87], v[86:87], v[98:99]
	v_pk_add_f32 v[80:81], v[80:81], v[80:81] op_sel:[0,1] op_sel_hi:[1,0]
	v_pk_add_f32 v[82:83], v[82:83], v[86:87]
	v_mul_f32_e32 v87, v93, v93
	v_add_f32_e32 v86, v82, v83
	v_mul_f32_e32 v82, v92, v92
	v_mov_b32_e32 v81, v82
	v_pk_add_f32 v[82:83], v[84:85], v[84:85] op_sel:[0,1] op_sel_hi:[1,0]
	v_mul_f32_e32 v84, v91, v91
	v_mov_b32_e32 v83, v87
	v_pk_add_f32 v[80:81], v[80:81], v[82:83]
	v_mul_f32_e32 v82, v89, v89
	v_mul_f32_e32 v92, v94, v94
	v_mul_f32_e32 v93, v95, v95
	v_pk_fma_f32 v[82:83], v[88:89], v[88:89], v[82:83] op_sel_hi:[1,1,0]
	v_pk_fma_f32 v[84:85], v[90:91], v[90:91], v[84:85] op_sel_hi:[1,1,0]
	v_mov_b32_e32 v83, v92
	v_mov_b32_e32 v85, v93
	v_pk_add_f32 v[82:83], v[82:83], v[84:85]
	s_and_b32 s16, s16, 14
	v_pk_add_f32 v[80:81], v[80:81], v[82:83]
	s_or_b32 s16, s16, s63
	v_add_f32_e32 v80, v80, v81
	s_ashr_i32 s17, s16, 31
	v_add_f32_dpp v82, v86, v86 quad_perm:[1,0,3,2] row_mask:0xf bank_mask:0xf bound_ctrl:1
	v_add_f32_dpp v83, v80, v80 quad_perm:[1,0,3,2] row_mask:0xf bank_mask:0xf bound_ctrl:1
	s_add_i32 s18, s91, s73
	s_lshl_b64 s[16:17], s[16:17], 9
	v_lshl_add_u64 v[80:81], v[154:155], 0, s[16:17]
	v_cndmask_b32_e64 v82, v83, v82, s[12:13]
	v_mov_b32_e32 v83, s18
	global_store_dwordx2 v[80:81], v[82:83], off sc1
.LBB0_1027:
	s_cmp_eq_u32 s80, 5
	s_cbranch_scc1 .LBB0_989
	s_andn2_b64 vcc, exec, s[14:15]
	s_cbranch_vccnz .LBB0_989
	s_add_i32 s16, s91, -1
	s_and_b32 s14, s16, 7
	s_or_b32 s14, s14, s81
	s_ashr_i32 s15, s14, 31
	s_lshl_b64 s[14:15], s[14:15], 10
	s_add_i32 s91, s91, s21
	v_lshl_add_u64 v[84:85], v[152:153], 0, s[14:15]
	s_mov_b32 s17, 0
	s_waitcnt vmcnt(0) lgkmcnt(0)
	v_mov_b64_e32 v[80:81], v[160:161]
	v_mov_b64_e32 v[82:83], v[158:159]
